# grid barrier: all waiting workgroups poll the XCD-leader arrival counter against (generation+1)*#XCDs instead of the generation word bumped after the last leader's atomic has returned
# baseline (speedup 1.0000x reference)
.LBB0_155:
	s_or_b64 exec, exec, s[8:9]
	v_cvt_f32_u32_e32 v5, v2
	s_waitcnt vmcnt(0)
	v_readfirstlane_b32 s6, v4
	v_sub_u32_e32 v4, 0, v2
	v_rcp_iflag_f32_e32 v5, v5
	v_add_u32_e32 v6, s6, v1
	v_mul_f32_e32 v5, 0x4f7ffffe, v5
	v_cvt_u32_f32_e32 v5, v5
	v_mul_lo_u32 v1, v4, v5
	v_mul_hi_u32 v1, v5, v1
	v_add_u32_e32 v1, v5, v1
	v_mul_hi_u32 v1, v6, v1
	v_mul_lo_u32 v4, v1, v2
	v_sub_u32_e32 v4, v6, v4
	v_add_u32_e32 v5, 1, v1
	v_cmp_ge_u32_e32 vcc, v4, v2
	s_nop 1
	v_cndmask_b32_e32 v1, v1, v5, vcc
	v_sub_u32_e32 v5, v4, v2
	v_cndmask_b32_e32 v4, v4, v5, vcc
	v_add_u32_e32 v5, 1, v1
	v_cmp_ge_u32_e32 vcc, v4, v2
	v_add_u32_e32 v4, 1, v6
	s_nop 0
	v_cndmask_b32_e32 v1, v1, v5, vcc
	v_mul_lo_u32 v5, v2, v1
	v_add_u32_e32 v2, v5, v2
	v_cmp_ne_u32_e32 vcc, v4, v2
	s_and_saveexec_b64 s[6:7], vcc
	s_xor_b64 s[6:7], exec, s[6:7]
	s_cbranch_execz .LBB0_169
	s_waitcnt lgkmcnt(0)
	v_add_u32_e32 v1, 1, v1
	v_mul_lo_u32 v1, v1, v0
	s_add_u32 s12, s2, 0x3783400
	s_addc_u32 s13, s3, 0
	global_load_dword v0, v3, s[12:13] sc1
	s_waitcnt vmcnt(0)
	v_cmp_lt_u32_e32 vcc, v0, v1
	s_and_saveexec_b64 s[8:9], vcc
	s_cbranch_execz .LBB0_168
	s_add_u32 s10, s2, 0x3780200
	s_addc_u32 s11, s3, 0
	s_mov_b32 s21, 1
	s_mov_b64 s[14:15], 0
	s_branch .LBB0_159

.LBB0_161:
	global_load_dword v0, v3, s[12:13] sc1
	s_add_i32 s21, s21, 1
	s_mov_b64 s[22:23], -1
	s_waitcnt vmcnt(0)
	v_cmp_ge_u32_e32 vcc, v0, v1
	s_orn2_b64 s[18:19], vcc, exec
	s_branch .LBB0_158

.LBB0_172:
	s_or_b64 exec, exec, s[8:9]
	v_cvt_f32_u32_e32 v4, v0
	s_waitcnt vmcnt(0)
	v_readfirstlane_b32 s6, v2
	s_mov_b64 s[10:11], -1
	v_rcp_iflag_f32_e32 v4, v4
	v_add_u32_e32 v1, s6, v1
	v_add_u32_e32 v5, 1, v1
	s_add_u32 s6, s2, 0x3783500
	v_mul_f32_e32 v2, 0x4f7ffffe, v4
	v_cvt_u32_f32_e32 v2, v2
	v_sub_u32_e32 v4, 0, v0
	s_addc_u32 s7, s3, 0
	v_mul_lo_u32 v4, v4, v2
	v_mul_hi_u32 v4, v2, v4
	v_add_u32_e32 v2, v2, v4
	v_mul_hi_u32 v2, v1, v2
	v_mul_lo_u32 v4, v2, v0
	v_sub_u32_e32 v1, v1, v4
	v_add_u32_e32 v6, 1, v2
	v_cmp_ge_u32_e32 vcc, v1, v0
	v_sub_u32_e32 v4, v1, v0
	s_nop 0
	v_cndmask_b32_e32 v2, v2, v6, vcc
	v_cndmask_b32_e32 v1, v1, v4, vcc
	v_add_u32_e32 v4, 1, v2
	v_cmp_ge_u32_e32 vcc, v1, v0
	s_nop 1
	v_cndmask_b32_e32 v2, v2, v4, vcc
	v_mul_lo_u32 v1, v0, v2
	v_add_u32_e32 v0, v1, v0
	v_cmp_ne_u32_e32 vcc, v5, v0
	v_mov_b32_e32 v4, v0
	v_mov_b64_e32 v[0:1], s[6:7]
	s_and_saveexec_b64 s[8:9], vcc
	s_cbranch_execz .LBB0_184
	global_load_dword v0, v3, s[6:7] offset:-256 sc1
	s_mov_b64 s[14:15], 0
	s_waitcnt vmcnt(0)
	v_cmp_lt_u32_e32 vcc, v0, v4
	s_and_saveexec_b64 s[12:13], vcc
	s_cbranch_execz .LBB0_183
	s_add_u32 s10, s2, 0x3780200
	s_addc_u32 s11, s3, 0
	s_mov_b32 s21, 1
	s_mov_b64 s[2:3], 0
	s_branch .LBB0_176

.LBB0_178:
	global_load_dword v0, v3, s[6:7] offset:-256 sc1
	s_add_i32 s21, s21, 1
	s_mov_b64 s[18:19], -1
	s_waitcnt vmcnt(0)
	v_cmp_ge_u32_e32 vcc, v0, v4
	s_orn2_b64 s[16:17], vcc, exec
	s_branch .LBB0_175

.LBB0_1177:
	s_or_b64 exec, exec, s[8:9]
	v_cvt_f32_u32_e32 v5, v2
	s_waitcnt vmcnt(0)
	v_readfirstlane_b32 s6, v4
	v_sub_u32_e32 v4, 0, v2
	v_rcp_iflag_f32_e32 v5, v5
	v_add_u32_e32 v6, s6, v1
	v_mul_f32_e32 v5, 0x4f7ffffe, v5
	v_cvt_u32_f32_e32 v5, v5
	v_mul_lo_u32 v1, v4, v5
	v_mul_hi_u32 v1, v5, v1
	v_add_u32_e32 v1, v5, v1
	v_mul_hi_u32 v1, v6, v1
	v_mul_lo_u32 v4, v1, v2
	v_sub_u32_e32 v4, v6, v4
	v_add_u32_e32 v5, 1, v1
	v_cmp_ge_u32_e32 vcc, v4, v2
	s_nop 1
	v_cndmask_b32_e32 v1, v1, v5, vcc
	v_sub_u32_e32 v5, v4, v2
	v_cndmask_b32_e32 v4, v4, v5, vcc
	v_add_u32_e32 v5, 1, v1
	v_cmp_ge_u32_e32 vcc, v4, v2
	v_add_u32_e32 v4, 1, v6
	s_nop 0
	v_cndmask_b32_e32 v1, v1, v5, vcc
	v_mul_lo_u32 v5, v2, v1
	v_add_u32_e32 v2, v5, v2
	v_cmp_ne_u32_e32 vcc, v4, v2
	s_and_saveexec_b64 s[6:7], vcc
	s_xor_b64 s[6:7], exec, s[6:7]
	s_cbranch_execz .LBB0_1191
	s_waitcnt lgkmcnt(0)
	v_add_u32_e32 v1, 1, v1
	v_mul_lo_u32 v1, v1, v0
	s_add_u32 s12, s2, 0x3783400
	s_addc_u32 s13, s3, 0
	global_load_dword v0, v3, s[12:13] sc1
	s_waitcnt vmcnt(0)
	v_cmp_lt_u32_e32 vcc, v0, v1
	s_and_saveexec_b64 s[8:9], vcc
	s_cbranch_execz .LBB0_1190
	s_add_u32 s10, s2, 0x3780200
	s_addc_u32 s11, s3, 0
	s_mov_b32 s24, 1
	s_mov_b64 s[14:15], 0
	s_branch .LBB0_1181

.LBB0_1183:
	global_load_dword v0, v3, s[12:13] sc1
	s_add_i32 s24, s24, 1
	s_mov_b64 s[20:21], -1
	s_waitcnt vmcnt(0)
	v_cmp_ge_u32_e32 vcc, v0, v1
	s_orn2_b64 s[18:19], vcc, exec
	s_branch .LBB0_1180

.LBB0_1194:
	s_or_b64 exec, exec, s[8:9]
	s_waitcnt vmcnt(0)
	v_readfirstlane_b32 s6, v2
	v_cvt_f32_u32_e32 v2, v0
	v_sub_u32_e32 v4, 0, v0
	v_add_u32_e32 v1, s6, v1
	s_add_u32 s6, s2, 0x3783500
	v_rcp_iflag_f32_e32 v2, v2
	s_addc_u32 s7, s3, 0
	s_mov_b64 s[10:11], -1
	v_mul_f32_e32 v2, 0x4f7ffffe, v2
	v_cvt_u32_f32_e32 v2, v2
	v_mul_lo_u32 v4, v4, v2
	v_mul_hi_u32 v4, v2, v4
	v_add_u32_e32 v2, v2, v4
	v_mul_hi_u32 v2, v1, v2
	v_mul_lo_u32 v4, v2, v0
	v_sub_u32_e32 v4, v1, v4
	v_cmp_ge_u32_e32 vcc, v4, v0
	v_add_u32_e32 v5, 1, v2
	v_add_u32_e32 v1, 1, v1
	v_cndmask_b32_e32 v2, v2, v5, vcc
	v_sub_u32_e32 v5, v4, v0
	v_cndmask_b32_e32 v4, v4, v5, vcc
	v_cmp_ge_u32_e32 vcc, v4, v0
	v_add_u32_e32 v4, 1, v2
	s_nop 0
	v_cndmask_b32_e32 v2, v2, v4, vcc
	v_mul_lo_u32 v4, v0, v2
	v_add_u32_e32 v0, v4, v0
	v_cmp_ne_u32_e32 vcc, v1, v0
	v_mov_b32_e32 v4, v0
	v_mov_b64_e32 v[0:1], s[6:7]
	s_and_saveexec_b64 s[8:9], vcc
	s_cbranch_execz .LBB0_1206
	global_load_dword v0, v3, s[6:7] offset:-256 sc1
	s_mov_b64 s[14:15], 0
	s_waitcnt vmcnt(0)
	v_cmp_lt_u32_e32 vcc, v0, v4
	s_and_saveexec_b64 s[12:13], vcc
	s_cbranch_execz .LBB0_1205
	s_add_u32 s10, s2, 0x3780200
	s_addc_u32 s11, s3, 0
	s_mov_b32 s22, 1
	s_mov_b64 s[2:3], 0
	s_branch .LBB0_1198

.LBB0_1200:
	global_load_dword v0, v3, s[6:7] offset:-256 sc1
	s_add_i32 s22, s22, 1
	s_mov_b64 s[18:19], -1
	s_waitcnt vmcnt(0)
	v_cmp_ge_u32_e32 vcc, v0, v4
	s_orn2_b64 s[16:17], vcc, exec
	s_branch .LBB0_1197
